# v5 + causal attention loop: LDS fragment reads software-pipelined 4 deep (QK, PV early, PV late), counted lgkmcnt
# speedup vs baseline: 1.0135x; 1.0009x over previous
.LBB0_1322:
	s_cmp_lg_u32 s88, 0
	s_cselect_b64 s[90:91], -1, 0
	s_and_b64 s[90:91], s[20:21], s[90:91]
	s_andn2_b64 vcc, exec, s[90:91]
	s_cbranch_vccnz .LBB0_1324
	s_mul_i32 s33, s87, 0x4800
	v_add_u32_e32 v72, s33, v151
	ds_read_b128 v[64:67], v72 offset:51200
	ds_read_b128 v[68:71], v72 offset:55808
	ds_read_b128 v[76:79], v72 offset:60416
	ds_read_b128 v[168:171], v72 offset:65024
	s_waitcnt lgkmcnt(3)
	v_mfma_f32_32x32x16_bf16 v[48:63], v[64:67], v[92:95], v[48:63]
	ds_read_b128 v[64:67], v72 offset:51232
	s_waitcnt lgkmcnt(3)
	v_mfma_f32_32x32x16_bf16 v[32:47], v[68:71], v[92:95], v[32:47]
	ds_read_b128 v[68:71], v72 offset:55840
	s_waitcnt lgkmcnt(3)
	v_mfma_f32_32x32x16_bf16 v[16:31], v[76:79], v[92:95], v[16:31]
	ds_read_b128 v[76:79], v72 offset:60448
	s_waitcnt lgkmcnt(3)
	v_mfma_f32_32x32x16_bf16 v[0:15], v[168:171], v[92:95], v[0:15]
	ds_read_b128 v[168:171], v72 offset:65056
	s_waitcnt lgkmcnt(3)
	v_mfma_f32_32x32x16_bf16 v[48:63], v[64:67], v[88:91], v[48:63]
	ds_read_b128 v[64:67], v72 offset:51264
	s_waitcnt lgkmcnt(3)
	v_mfma_f32_32x32x16_bf16 v[32:47], v[68:71], v[88:91], v[32:47]
	ds_read_b128 v[68:71], v72 offset:55872
	s_waitcnt lgkmcnt(3)
	v_mfma_f32_32x32x16_bf16 v[16:31], v[76:79], v[88:91], v[16:31]
	ds_read_b128 v[76:79], v72 offset:60480
	s_waitcnt lgkmcnt(3)
	v_mfma_f32_32x32x16_bf16 v[0:15], v[168:171], v[88:91], v[0:15]
	ds_read_b128 v[168:171], v72 offset:65088
	s_waitcnt lgkmcnt(3)
	v_mfma_f32_32x32x16_bf16 v[48:63], v[64:67], v[84:87], v[48:63]
	ds_read_b128 v[64:67], v72 offset:51296
	s_waitcnt lgkmcnt(3)
	v_mfma_f32_32x32x16_bf16 v[32:47], v[68:71], v[84:87], v[32:47]
	ds_read_b128 v[68:71], v72 offset:55904
	s_waitcnt lgkmcnt(3)
	v_mfma_f32_32x32x16_bf16 v[16:31], v[76:79], v[84:87], v[16:31]
	ds_read_b128 v[76:79], v72 offset:60512
	s_waitcnt lgkmcnt(3)
	v_mfma_f32_32x32x16_bf16 v[0:15], v[168:171], v[84:87], v[0:15]
	ds_read_b128 v[168:171], v72 offset:65120
	s_waitcnt lgkmcnt(3)
	v_mfma_f32_32x32x16_bf16 v[48:63], v[64:67], v[80:83], v[48:63]
	s_waitcnt lgkmcnt(2)
	v_mfma_f32_32x32x16_bf16 v[32:47], v[68:71], v[80:83], v[32:47]
	s_waitcnt lgkmcnt(1)
	v_mfma_f32_32x32x16_bf16 v[16:31], v[76:79], v[80:83], v[16:31]
	s_waitcnt lgkmcnt(0)
	v_mfma_f32_32x32x16_bf16 v[0:15], v[168:171], v[80:83], v[0:15]
	s_mov_b32 s88, 0
.LBB0_1324:
	s_sub_i32 s33, s84, 63
	s_cmp_gt_u32 s33, s54
	s_cbranch_scc1 .LBB0_1332
	v_xor_b32_e32 v64, 0x80000000, v242
	s_mulk_i32 s89, 0x6400
	v_add3_u32 v144, v215, s89, v201
	ds_read_b128 v[168:171], v144
	ds_read_b128 v[172:175], v144 offset:32
	ds_read_b128 v[176:179], v144 offset:64
	ds_read_b128 v[180:183], v144 offset:96
	v_mov_b32_e32 v65, v64
	v_mov_b32_e32 v66, v64
	v_mov_b32_e32 v67, v64
	v_mov_b32_e32 v68, v64
	v_mov_b32_e32 v69, v64
	v_mov_b32_e32 v70, v64
	v_mov_b32_e32 v71, v64
	v_mov_b32_e32 v72, v64
	v_mov_b32_e32 v73, v64
	v_mov_b32_e32 v74, v64
	v_mov_b32_e32 v75, v64
	v_mov_b32_e32 v76, v64
	v_mov_b32_e32 v77, v64
	v_mov_b32_e32 v78, v64
	v_mov_b32_e32 v79, v64
	s_nop 1
	s_waitcnt lgkmcnt(3)
	v_mfma_f32_32x32x16_bf16 v[80:95], v[168:171], v[96:99], v[64:79]
	ds_read_b128 v[168:171], v144 offset:128
	s_waitcnt lgkmcnt(3)
	v_mfma_f32_32x32x16_bf16 v[80:95], v[172:175], v[100:103], v[80:95]
	ds_read_b128 v[172:175], v144 offset:160
	s_waitcnt lgkmcnt(3)
	v_mfma_f32_32x32x16_bf16 v[80:95], v[176:179], v[104:107], v[80:95]
	ds_read_b128 v[176:179], v144 offset:192
	s_waitcnt lgkmcnt(3)
	v_mfma_f32_32x32x16_bf16 v[80:95], v[180:183], v[108:111], v[80:95]
	ds_read_b128 v[180:183], v144 offset:224
	s_waitcnt lgkmcnt(3)
	v_mfma_f32_32x32x16_bf16 v[80:95], v[168:171], v[112:115], v[80:95]
	ds_read_b128 v[168:171], v144 offset:256
	s_waitcnt lgkmcnt(3)
	v_mfma_f32_32x32x16_bf16 v[80:95], v[172:175], v[116:119], v[80:95]
	ds_read_b128 v[172:175], v144 offset:288
	s_waitcnt lgkmcnt(3)
	v_mfma_f32_32x32x16_bf16 v[80:95], v[176:179], v[120:123], v[80:95]
	ds_read_b128 v[176:179], v144 offset:320
	s_waitcnt lgkmcnt(3)
	v_mfma_f32_32x32x16_bf16 v[80:95], v[180:183], v[124:127], v[80:95]
	ds_read_b128 v[180:183], v144 offset:352
	s_waitcnt lgkmcnt(3)
	v_mfma_f32_32x32x16_bf16 v[80:95], v[168:171], v[128:131], v[80:95]
	ds_read_b128 v[168:171], v144 offset:12800
	s_waitcnt lgkmcnt(3)
	v_mfma_f32_32x32x16_bf16 v[80:95], v[172:175], v[132:135], v[80:95]
	ds_read_b128 v[172:175], v144 offset:12832
	s_waitcnt lgkmcnt(3)
	v_mfma_f32_32x32x16_bf16 v[80:95], v[176:179], v[136:139], v[80:95]
	ds_read_b128 v[176:179], v144 offset:12864
	s_waitcnt lgkmcnt(3)
	v_mfma_f32_32x32x16_bf16 v[80:95], v[180:183], v[140:143], v[80:95]
	ds_read_b128 v[180:183], v144 offset:12896
	s_waitcnt lgkmcnt(3)
	v_mfma_f32_32x32x16_bf16 v[64:79], v[168:171], v[96:99], v[64:79]
	ds_read_b128 v[168:171], v144 offset:12928
	s_waitcnt lgkmcnt(3)
	v_mfma_f32_32x32x16_bf16 v[64:79], v[172:175], v[100:103], v[64:79]
	ds_read_b128 v[172:175], v144 offset:12960
	s_waitcnt lgkmcnt(3)
	v_mfma_f32_32x32x16_bf16 v[64:79], v[176:179], v[104:107], v[64:79]
	ds_read_b128 v[176:179], v144 offset:12992
	s_waitcnt lgkmcnt(3)
	v_mfma_f32_32x32x16_bf16 v[64:79], v[180:183], v[108:111], v[64:79]
	ds_read_b128 v[180:183], v144 offset:13024
	s_waitcnt lgkmcnt(3)
	v_mfma_f32_32x32x16_bf16 v[64:79], v[168:171], v[112:115], v[64:79]
	ds_read_b128 v[168:171], v144 offset:13056
	s_waitcnt lgkmcnt(3)
	v_mfma_f32_32x32x16_bf16 v[64:79], v[172:175], v[116:119], v[64:79]
	ds_read_b128 v[172:175], v144 offset:13088
	s_waitcnt lgkmcnt(3)
	v_mfma_f32_32x32x16_bf16 v[64:79], v[176:179], v[120:123], v[64:79]
	ds_read_b128 v[176:179], v144 offset:13120
	s_waitcnt lgkmcnt(3)
	v_mfma_f32_32x32x16_bf16 v[64:79], v[180:183], v[124:127], v[64:79]
	ds_read_b128 v[180:183], v144 offset:13152
	s_waitcnt lgkmcnt(3)
	v_mfma_f32_32x32x16_bf16 v[64:79], v[168:171], v[128:131], v[64:79]
	s_waitcnt lgkmcnt(2)
	v_mfma_f32_32x32x16_bf16 v[64:79], v[172:175], v[132:135], v[64:79]
	s_waitcnt lgkmcnt(1)
	v_mfma_f32_32x32x16_bf16 v[64:79], v[176:179], v[136:139], v[64:79]
	s_waitcnt lgkmcnt(0)
	v_mfma_f32_32x32x16_bf16 v[64:79], v[180:183], v[140:143], v[64:79]
	s_cmp_le_u32 s84, s48
	s_cbranch_scc1 .LBB0_1327
	v_add_u32_e32 v144, s84, v200
	v_subrev_u32_e32 v168, 63, v144
	v_cmp_gt_u32_e32 vcc, v168, v153
	s_nop 1
	v_cndmask_b32_e32 v169, v80, v239, vcc
	v_cmp_lt_u32_e32 vcc, v168, v153
	v_subrev_u32_e32 v168, 61, v144
	s_nop 0
	v_cndmask_b32_e32 v80, v169, v80, vcc
	v_cndmask_b32_e32 v81, v239, v81, vcc
	v_cmp_le_u32_e32 vcc, v168, v153
	v_subrev_u32_e32 v168, 60, v144
	s_nop 0
	v_cndmask_b32_e32 v82, v239, v82, vcc
	v_cmp_le_u32_e32 vcc, v168, v153
	v_subrev_u32_e32 v168, 55, v144
	s_nop 0
	v_cndmask_b32_e32 v83, v239, v83, vcc
	v_cmp_le_u32_e32 vcc, v168, v153
	v_subrev_u32_e32 v168, 54, v144
	s_nop 0
	v_cndmask_b32_e32 v84, v239, v84, vcc
	v_cmp_le_u32_e32 vcc, v168, v153
	v_subrev_u32_e32 v168, 53, v144
	s_nop 0
	v_cndmask_b32_e32 v85, v239, v85, vcc
	v_cmp_le_u32_e32 vcc, v168, v153
	v_subrev_u32_e32 v168, 52, v144
	s_nop 0
	v_cndmask_b32_e32 v86, v239, v86, vcc
	v_cmp_le_u32_e32 vcc, v168, v153
	v_subrev_u32_e32 v168, 47, v144
	s_nop 0
	v_cndmask_b32_e32 v87, v239, v87, vcc
	v_cmp_le_u32_e32 vcc, v168, v153
	v_subrev_u32_e32 v168, 46, v144
	s_nop 0
	v_cndmask_b32_e32 v88, v239, v88, vcc
	v_cmp_le_u32_e32 vcc, v168, v153
	v_subrev_u32_e32 v168, 45, v144
	s_nop 0
	v_cndmask_b32_e32 v89, v239, v89, vcc
	v_cmp_le_u32_e32 vcc, v168, v153
	v_subrev_u32_e32 v168, 44, v144
	s_nop 0
	v_cndmask_b32_e32 v90, v239, v90, vcc
	v_cmp_le_u32_e32 vcc, v168, v153
	v_subrev_u32_e32 v168, 39, v144
	s_nop 0
	v_cndmask_b32_e32 v91, v239, v91, vcc
	v_cmp_le_u32_e32 vcc, v168, v153
	v_subrev_u32_e32 v168, 38, v144
	s_nop 0
	v_cndmask_b32_e32 v92, v239, v92, vcc
	v_cmp_le_u32_e32 vcc, v168, v153
	v_subrev_u32_e32 v168, 37, v144
	s_nop 0
	v_cndmask_b32_e32 v93, v239, v93, vcc
	v_cmp_le_u32_e32 vcc, v168, v153
	v_subrev_u32_e32 v168, 36, v144
	s_nop 0
	v_cndmask_b32_e32 v94, v239, v94, vcc
	v_cmp_le_u32_e32 vcc, v168, v153
	v_subrev_u32_e32 v168, 31, v144
	s_nop 0
	v_cndmask_b32_e32 v95, v239, v95, vcc
	v_cmp_le_u32_e32 vcc, v168, v153
	v_subrev_u32_e32 v168, 30, v144
	s_nop 0
	v_cndmask_b32_e32 v64, v239, v64, vcc
	v_cmp_le_u32_e32 vcc, v168, v153
	v_subrev_u32_e32 v168, 29, v144
	s_nop 0
	v_cndmask_b32_e32 v65, v239, v65, vcc
	v_cmp_le_u32_e32 vcc, v168, v153
	v_subrev_u32_e32 v168, 28, v144
	s_nop 0
	v_cndmask_b32_e32 v66, v239, v66, vcc
	v_cmp_le_u32_e32 vcc, v168, v153
	v_subrev_u32_e32 v168, 23, v144
	s_nop 0
	v_cndmask_b32_e32 v67, v239, v67, vcc
	v_cmp_le_u32_e32 vcc, v168, v153
	v_subrev_u32_e32 v168, 22, v144
	s_nop 0
	v_cndmask_b32_e32 v68, v239, v68, vcc
	v_cmp_le_u32_e32 vcc, v168, v153
	v_subrev_u32_e32 v168, 21, v144
	s_nop 0
	v_cndmask_b32_e32 v69, v239, v69, vcc
	v_cmp_le_u32_e32 vcc, v168, v153
	v_subrev_u32_e32 v168, 20, v144
	s_nop 0
	v_cndmask_b32_e32 v70, v239, v70, vcc
	v_cmp_le_u32_e32 vcc, v168, v153
	v_add_u32_e32 v168, -15, v144
	s_nop 0
	v_cndmask_b32_e32 v71, v239, v71, vcc
	v_cmp_le_u32_e32 vcc, v168, v153
	v_add_u32_e32 v168, -14, v144
	s_nop 0
	v_cndmask_b32_e32 v72, v239, v72, vcc
	v_cmp_le_u32_e32 vcc, v168, v153
	v_add_u32_e32 v168, -13, v144
	s_nop 0
	v_cndmask_b32_e32 v73, v239, v73, vcc
	v_cmp_le_u32_e32 vcc, v168, v153
	v_add_u32_e32 v168, -12, v144
	s_nop 0
	v_cndmask_b32_e32 v74, v239, v74, vcc
	v_cmp_le_u32_e32 vcc, v168, v153
	v_add_u32_e32 v168, -7, v144
	s_nop 0
	v_cndmask_b32_e32 v75, v239, v75, vcc
	v_cmp_le_u32_e32 vcc, v168, v153
	v_add_u32_e32 v168, -6, v144
	s_nop 0
	v_cndmask_b32_e32 v76, v239, v76, vcc
	v_cmp_le_u32_e32 vcc, v168, v153
	v_add_u32_e32 v168, -5, v144
	v_add_u32_e32 v144, -4, v144
	v_cndmask_b32_e32 v77, v239, v77, vcc
	v_cmp_le_u32_e32 vcc, v168, v153
	s_nop 1
	v_cndmask_b32_e32 v78, v239, v78, vcc
	v_cmp_le_u32_e32 vcc, v144, v153
	s_nop 1
	v_cndmask_b32_e32 v79, v239, v79, vcc

.LBB0_1329:
	v_exp_f32_e32 v168, v80
	v_exp_f32_e32 v169, v81
	v_exp_f32_e32 v170, v82
	v_exp_f32_e32 v171, v83
	v_exp_f32_e32 v172, v84
	v_exp_f32_e32 v173, v85
	v_exp_f32_e32 v174, v86
	v_exp_f32_e32 v175, v87
	v_exp_f32_e32 v176, v88
	v_exp_f32_e32 v177, v89
	v_exp_f32_e32 v178, v90
	v_exp_f32_e32 v179, v91
	v_exp_f32_e32 v180, v92
	v_exp_f32_e32 v181, v93
	v_exp_f32_e32 v182, v94
	v_exp_f32_e32 v183, v95
	v_exp_f32_e32 v64, v64
	v_exp_f32_e32 v65, v65
	v_exp_f32_e32 v66, v66
	v_exp_f32_e32 v67, v67
	v_exp_f32_e32 v68, v68
	v_exp_f32_e32 v69, v69
	v_exp_f32_e32 v70, v70
	v_exp_f32_e32 v71, v71
	v_exp_f32_e32 v72, v72
	v_exp_f32_e32 v73, v73
	v_exp_f32_e32 v74, v74
	v_exp_f32_e32 v75, v75
	v_exp_f32_e32 v76, v76
	v_exp_f32_e32 v77, v77
	v_exp_f32_e32 v78, v78
	v_exp_f32_e32 v79, v79
	v_cvt_pk_bf16_f32 v92, v168, v169
	v_cvt_pk_bf16_f32 v93, v170, v171
	v_cvt_pk_bf16_f32 v94, v172, v173
	v_cvt_pk_bf16_f32 v95, v174, v175
	v_cvt_pk_bf16_f32 v88, v176, v177
	v_cvt_pk_bf16_f32 v89, v178, v179
	v_cvt_pk_bf16_f32 v90, v180, v181
	v_cvt_pk_bf16_f32 v91, v182, v183
	v_cvt_pk_bf16_f32 v84, v64, v65
	v_cvt_pk_bf16_f32 v85, v66, v67
	v_cvt_pk_bf16_f32 v86, v68, v69
	v_cvt_pk_bf16_f32 v87, v70, v71
	v_cvt_pk_bf16_f32 v80, v72, v73
	v_cvt_pk_bf16_f32 v81, v74, v75
	v_cvt_pk_bf16_f32 v82, v76, v77
	v_cvt_pk_bf16_f32 v83, v78, v79
	s_andn2_b64 vcc, exec, s[38:39]
	s_mov_b32 s88, 1
	s_cbranch_vccnz .LBB0_1331
	s_mul_i32 s33, s86, 0x4800
	v_add3_u32 v144, v215, s33, v149
	ds_read_b128 v[186:189], v144 offset:51200
	ds_read_b128 v[190:193], v144 offset:55808
	ds_read_b128 v[194:197], v144 offset:60416
	ds_read_b128 v[244:247], v144 offset:65024
	s_waitcnt lgkmcnt(3)
	v_mfma_f32_32x32x16_bf16 v[48:63], v[186:189], v[92:95], v[48:63]
	ds_read_b128 v[186:189], v144 offset:51232
	s_waitcnt lgkmcnt(3)
	v_mfma_f32_32x32x16_bf16 v[32:47], v[190:193], v[92:95], v[32:47]
	ds_read_b128 v[190:193], v144 offset:55840
	s_waitcnt lgkmcnt(3)
	v_mfma_f32_32x32x16_bf16 v[16:31], v[194:197], v[92:95], v[16:31]
	ds_read_b128 v[194:197], v144 offset:60448
	s_waitcnt lgkmcnt(3)
	v_mfma_f32_32x32x16_bf16 v[0:15], v[244:247], v[92:95], v[0:15]
	ds_read_b128 v[244:247], v144 offset:65056
	s_waitcnt lgkmcnt(3)
	v_mfma_f32_32x32x16_bf16 v[48:63], v[186:189], v[88:91], v[48:63]
	ds_read_b128 v[186:189], v144 offset:51264
	s_waitcnt lgkmcnt(3)
	v_mfma_f32_32x32x16_bf16 v[32:47], v[190:193], v[88:91], v[32:47]
	ds_read_b128 v[190:193], v144 offset:55872
	s_waitcnt lgkmcnt(3)
	v_mfma_f32_32x32x16_bf16 v[16:31], v[194:197], v[88:91], v[16:31]
	ds_read_b128 v[194:197], v144 offset:60480
	s_waitcnt lgkmcnt(3)
	v_mfma_f32_32x32x16_bf16 v[0:15], v[244:247], v[88:91], v[0:15]
	ds_read_b128 v[244:247], v144 offset:65088
	s_waitcnt lgkmcnt(3)
	v_mfma_f32_32x32x16_bf16 v[48:63], v[186:189], v[84:87], v[48:63]
	ds_read_b128 v[186:189], v144 offset:51296
	s_waitcnt lgkmcnt(3)
	v_mfma_f32_32x32x16_bf16 v[32:47], v[190:193], v[84:87], v[32:47]
	ds_read_b128 v[190:193], v144 offset:55904
	s_waitcnt lgkmcnt(3)
	v_mfma_f32_32x32x16_bf16 v[16:31], v[194:197], v[84:87], v[16:31]
	ds_read_b128 v[194:197], v144 offset:60512
	s_waitcnt lgkmcnt(3)
	v_mfma_f32_32x32x16_bf16 v[0:15], v[244:247], v[84:87], v[0:15]
	ds_read_b128 v[244:247], v144 offset:65120
	s_waitcnt lgkmcnt(3)
	v_mfma_f32_32x32x16_bf16 v[48:63], v[186:189], v[80:83], v[48:63]
	s_waitcnt lgkmcnt(2)
	v_mfma_f32_32x32x16_bf16 v[32:47], v[190:193], v[80:83], v[32:47]
	s_waitcnt lgkmcnt(1)
	v_mfma_f32_32x32x16_bf16 v[16:31], v[194:197], v[80:83], v[16:31]
	s_waitcnt lgkmcnt(0)
	v_mfma_f32_32x32x16_bf16 v[0:15], v[244:247], v[80:83], v[0:15]
	s_mov_b32 s88, 0
